# grid barrier: all workgroups poll the TOP arrival counter against (gen+1)*nx; no generation word, no read-back by the last leader
# baseline (speedup 1.0000x reference)
.LBB0_353:
	s_or_b64 exec, exec, s[20:21]
	v_cvt_f32_u32_e32 v5, v3
	s_waitcnt vmcnt(0)
	v_readfirstlane_b32 s4, v4
	v_sub_u32_e32 v4, 0, v3
	v_rcp_iflag_f32_e32 v5, v5
	v_add_u32_e32 v6, s4, v0
	v_mul_f32_e32 v5, 0x4f7ffffe, v5
	v_cvt_u32_f32_e32 v5, v5
	v_mul_lo_u32 v0, v4, v5
	v_mul_hi_u32 v0, v5, v0
	v_add_u32_e32 v0, v5, v0
	v_mul_hi_u32 v0, v6, v0
	v_mul_lo_u32 v4, v0, v3
	v_sub_u32_e32 v4, v6, v4
	v_add_u32_e32 v5, 1, v0
	v_cmp_ge_u32_e32 vcc, v4, v3
	s_nop 1
	v_cndmask_b32_e32 v0, v0, v5, vcc
	v_sub_u32_e32 v5, v4, v3
	v_cndmask_b32_e32 v4, v4, v5, vcc
	v_add_u32_e32 v5, 1, v0
	v_cmp_ge_u32_e32 vcc, v4, v3
	v_add_u32_e32 v4, 1, v6
	s_nop 0
	v_cndmask_b32_e32 v0, v0, v5, vcc
	v_mul_lo_u32 v5, v3, v0
	v_add_u32_e32 v3, v5, v3
	v_cmp_ne_u32_e32 vcc, v4, v3
	s_and_saveexec_b64 s[4:5], vcc
	s_xor_b64 s[20:21], exec, s[4:5]
	s_cbranch_execz .LBB0_368
	v_readlane_b32 s4, v254, 46
	v_readlane_b32 s5, v254, 47
	s_waitcnt lgkmcnt(0)
	s_nop 3
	v_add_u32_e32 v7, 1, v0
	v_mul_lo_u32 v7, v7, v2
	global_load_dword v2, v1, s[4:5] sc1
	s_waitcnt vmcnt(0)
	v_cmp_lt_u32_e32 vcc, v2, v7
	s_and_saveexec_b64 s[22:23], vcc
	s_cbranch_execz .LBB0_367
	s_mov_b32 s4, 1
	s_mov_b64 s[24:25], 0
	s_branch .LBB0_357

.LBB0_361:
	v_readlane_b32 s6, v254, 46
	v_readlane_b32 s7, v254, 47
	s_add_i32 s4, s4, 1
	s_mov_b64 s[34:35], -1
	s_nop 2
	global_load_dword v2, v1, s[6:7] sc1
	s_waitcnt vmcnt(0)
	v_cmp_ge_u32_e32 vcc, v2, v7
	s_orn2_b64 s[28:29], vcc, exec
	s_branch .LBB0_356

.LBB0_371:
	s_or_b64 exec, exec, s[22:23]
	s_waitcnt vmcnt(0)
	v_readfirstlane_b32 s4, v3
	v_sub_u32_e32 v4, 0, v2
	s_mov_b64 s[22:23], 0
	v_add_u32_e32 v3, s4, v0
	v_cvt_f32_u32_e32 v0, v2
	v_readlane_b32 s4, v254, 48
	v_readlane_b32 s5, v254, 49
	v_rcp_iflag_f32_e32 v0, v0
	s_nop 0
	v_mul_f32_e32 v0, 0x4f7ffffe, v0
	v_cvt_u32_f32_e32 v0, v0
	v_mul_lo_u32 v4, v4, v0
	v_mul_hi_u32 v4, v0, v4
	v_add_u32_e32 v0, v0, v4
	v_mul_hi_u32 v0, v3, v0
	v_mul_lo_u32 v4, v0, v2
	v_sub_u32_e32 v4, v3, v4
	v_cmp_ge_u32_e32 vcc, v4, v2
	v_add_u32_e32 v5, 1, v0
	v_add_u32_e32 v3, 1, v3
	v_cndmask_b32_e32 v0, v0, v5, vcc
	v_sub_u32_e32 v5, v4, v2
	v_cndmask_b32_e32 v4, v4, v5, vcc
	v_cmp_ge_u32_e32 vcc, v4, v2
	v_add_u32_e32 v4, 1, v0
	s_nop 0
	v_cndmask_b32_e32 v0, v0, v4, vcc
	v_mul_lo_u32 v4, v2, v0
	v_add_u32_e32 v2, v4, v2
	v_mov_b32_e32 v7, v2
	v_cmp_ne_u32_e32 vcc, v3, v2
	v_mov_b64_e32 v[2:3], s[4:5]
	s_and_saveexec_b64 s[20:21], vcc
	s_cbranch_execz .LBB0_383
	v_readlane_b32 s4, v254, 46
	v_readlane_b32 s5, v254, 47
	s_mov_b64 s[24:25], 0
	s_nop 3
	global_load_dword v2, v1, s[4:5] sc1
	s_waitcnt vmcnt(0)
	v_cmp_lt_u32_e32 vcc, v2, v7
	s_and_saveexec_b64 s[22:23], vcc
	s_cbranch_execz .LBB0_382
	s_mov_b32 s4, 1
	s_branch .LBB0_375
